# row passes: normmod x3 issue all gain/scale/shift loads up front (fresh VGPRs, one vmcnt wait) and final rmsnorm keeps its gain vector in registers, instead of per-group load-wait-store ladders
# speedup vs baseline: 1.0144x; 1.0091x over previous
; __device__ __forceinline__ unsigned pk2(float a, float b) { typedef __bf16 bf2_t __attribute__((ext_vector_type(2))); f32x2 v = {a, b}; return __builtin_bit_cast(unsigned, __builtin_convertvector(v, bf2_t)); }
; __device__ __forceinline__ void phase_normmod(const float* X, const float* g, const float* mod, int sh_off, int sc_off, bf16* U, int lane, int gw, int NGW, int rowEnd = MT) {
; #pragma unroll 1
;     for (int row = gw; row < rowEnd; row += 2 * NGW) { const int row2 = row + NGW;
;         const bool has2 = row2 < rowEnd; const int rB = has2 ? row2 : row;
;         const f32x4* xa = (const f32x4*)(X + (size_t)row * DM) + lane; const f32x4* xb = (const f32x4*)(X + (size_t)rB * DM) + lane; f32x4 va[4], vb[4]; float sa = 0.f, sb = 0.f;
; #pragma unroll
;         for (int j = 0; j < 4; ++j) { va[j] = xa[64 * j]; vb[j] = xb[64 * j]; }
; #pragma unroll
;         for (int j = 0; j < 4; ++j) { sa += (va[j].x * va[j].x + va[j].y * va[j].y) + (va[j].z * va[j].z + va[j].w * va[j].w); sb += (vb[j].x * vb[j].x + vb[j].y * vb[j].y) + (vb[j].z * vb[j].z + vb[j].w * vb[j].w); }
;         wave_sum2(sa, sb);
;         const float ra = rsqrtf(sa * (1.f / DM) + 1e-6f), rb = rsqrtf(sb * (1.f / DM) + 1e-6f);
;         const float* ma = mod + (size_t)(row >> 13) * NMODC; const float* mb = mod + (size_t)(rB >> 13) * NMODC;
; #pragma unroll
;         for (int j = 0; j < 4; ++j) { const int col = 4 * lane + 256 * j; const f32x4 gv = *(const f32x4*)(g + col);
;             { const f32x4 sc = *(const f32x4*)(ma + sc_off + col), sh = *(const f32x4*)(ma + sh_off + col); const f32x4 o = (va[j] * ra * gv) * (sc + 1.f) + sh; u32x2 w; w.x = pk2(o.x, o.y); w.y = pk2(o.z, o.w); *(u32x2*)(U + (size_t)row * DM + col) = w; }
;             if (has2) { const f32x4 sc = *(const f32x4*)(mb + sc_off + col), sh = *(const f32x4*)(mb + sh_off + col); const f32x4 o = (vb[j] * rb * gv) * (sc + 1.f) + sh; u32x2 w; w.x = pk2(o.x, o.y); w.y = pk2(o.z, o.w); *(u32x2*)(U + (size_t)rB * DM + col) = w; } }
.LBB0_591:
	s_add_i32 s15, s94, s4
	global_load_dwordx4 v[28:31], v[52:53], off
	global_load_dwordx4 v[20:23], v[52:53], off offset:1024
	global_load_dwordx4 v[4:7], v[52:53], off offset:3072
	global_load_dwordx4 v[12:15], v[52:53], off offset:2048
	s_cmp_lt_i32 s15, 0x10000
	s_cselect_b64 s[0:1], -1, 0
	s_and_b64 s[2:3], s[0:1], exec
	s_cselect_b32 s2, s15, s4
	s_ashr_i32 s3, s2, 31
	s_lshl_b64 s[16:17], s[2:3], 12
	v_lshl_add_u64 v[8:9], v[38:39], 0, s[16:17]
	global_load_dwordx4 v[24:27], v[8:9], off
	global_load_dwordx4 v[16:19], v[8:9], off offset:1024
	global_load_dwordx4 v[0:3], v[8:9], off offset:3072
	s_nop 0
	global_load_dwordx4 v[8:11], v[8:9], off offset:2048
	s_nop 0
	s_ashr_i32 s16, s4, 13
	s_mul_hi_i32 s17, s16, 0x9000
	s_mul_i32 s16, s16, 0x9000
	s_add_u32 s24, s84, s16
	s_addc_u32 s25, s85, s17
	s_ashr_i32 s16, s2, 13
	s_mul_hi_i32 s17, s16, 0x9000
	s_mul_i32 s16, s16, 0x9000
	s_add_u32 s16, s84, s16
	s_addc_u32 s17, s85, s17
	s_add_u32 s18, s24, 0x1000
	s_addc_u32 s19, s25, 0
	s_add_u32 s22, s16, 0x1000
	s_addc_u32 s23, s17, 0
	s_lshl_b64 s[20:21], s[2:3], 11
	s_add_u32 s20, s58, s20
	s_addc_u32 s21, s59, s21
	s_cmp_gt_i32 s15, 0xffff
	global_load_dwordx4 v[82:85], v[42:43], off
	global_load_dwordx4 v[86:89], v36, s[18:19]
	global_load_dwordx4 v[90:93], v36, s[24:25]
	global_load_dwordx4 v[94:97], v36, s[22:23]
	global_load_dwordx4 v[98:101], v36, s[16:17]
	global_load_dwordx4 v[102:105], v[42:43], off offset:1024
	v_lshlrev_b32_e32 v110, 2, v44
	global_load_dwordx4 v[106:109], v110, s[18:19]
	v_lshl_add_u64 v[116:117], s[24:25], 0, v[36:37]
	global_load_dwordx4 v[112:115], v[116:117], off offset:1024
	v_lshlrev_b32_e32 v122, 2, v44
	global_load_dwordx4 v[118:121], v122, s[22:23]
	global_load_dwordx4 v[124:127], v36, s[16:17] offset:1024
	global_load_dwordx4 v[152:155], v[42:43], off offset:2048
	v_lshlrev_b32_e32 v160, 2, v46
	global_load_dwordx4 v[156:159], v160, s[18:19]
	v_lshl_add_u64 v[162:163], s[24:25], 0, v[36:37]
	global_load_dwordx4 v[168:171], v[162:163], off offset:2048
	v_lshlrev_b32_e32 v176, 2, v46
	global_load_dwordx4 v[172:175], v176, s[22:23]
	global_load_dwordx4 v[178:181], v36, s[16:17] offset:2048
	global_load_dwordx4 v[182:185], v[42:43], off offset:3072
	v_lshlrev_b32_e32 v190, 2, v48
	global_load_dwordx4 v[186:189], v190, s[18:19]
	v_lshl_add_u64 v[196:197], s[24:25], 0, v[36:37]
	global_load_dwordx4 v[192:195], v[196:197], off offset:3072
	v_lshlrev_b32_e32 v202, 2, v48
	global_load_dwordx4 v[198:201], v202, s[22:23]
	global_load_dwordx4 v[204:207], v36, s[16:17] offset:3072
	s_waitcnt vmcnt(27)
	v_pk_mul_f32 v[56:57], v[30:31], v[30:31]
	v_pk_mul_f32 v[58:59], v[28:29], v[28:29]
	s_waitcnt vmcnt(26)
	v_pk_mul_f32 v[68:69], v[22:23], v[22:23]
	v_pk_mul_f32 v[70:71], v[20:21], v[20:21]
	v_pk_mov_b32 v[76:77], v[58:59], v[56:57] op_sel:[1,0]
	v_mov_b32_e32 v59, v57
	v_pk_mov_b32 v[56:57], v[70:71], v[68:69] op_sel:[1,0]
	v_mov_b32_e32 v71, v69
	s_waitcnt vmcnt(25)
	v_mul_f32_e32 v75, v7, v7
	s_waitcnt vmcnt(24)
	v_mul_f32_e32 v72, v13, v13
	v_mul_f32_e32 v74, v15, v15
	v_pk_add_f32 v[58:59], v[76:77], v[58:59]
	v_pk_add_f32 v[56:57], v[56:57], v[70:71]
	v_mul_f32_e32 v47, v4, v4
	v_mul_f32_e32 v49, v5, v5
	v_mul_f32_e32 v55, v6, v6
	v_pk_fma_f32 v[68:69], v[12:13], v[12:13], v[72:73] op_sel_hi:[1,1,0]
	v_pk_fma_f32 v[72:73], v[14:15], v[14:15], v[74:75] op_sel_hi:[1,1,0]
	v_pk_add_f32 v[58:59], v[58:59], v[58:59] op_sel:[0,1] op_sel_hi:[1,0]
	v_pk_add_f32 v[56:57], v[56:57], v[56:57] op_sel:[0,1] op_sel_hi:[1,0]
	v_mov_b32_e32 v69, v55
	v_mov_b32_e32 v73, v75
	v_mov_b32_e32 v59, v47
	v_mov_b32_e32 v57, v49
	v_pk_add_f32 v[68:69], v[68:69], v[72:73]
	v_pk_add_f32 v[56:57], v[58:59], v[56:57]
	s_waitcnt vmcnt(23)
	v_pk_mul_f32 v[70:71], v[24:25], v[24:25]
	v_pk_add_f32 v[56:57], v[56:57], v[68:69]
	v_pk_mul_f32 v[68:69], v[26:27], v[26:27]
	s_waitcnt vmcnt(22)
	v_pk_mul_f32 v[72:73], v[18:19], v[18:19]
	v_pk_mul_f32 v[74:75], v[16:17], v[16:17]
	v_pk_mov_b32 v[76:77], v[70:71], v[68:69] op_sel:[1,0]
	v_mov_b32_e32 v71, v69
	v_pk_mov_b32 v[68:69], v[74:75], v[72:73] op_sel:[1,0]
	v_mov_b32_e32 v75, v73
	v_mov_b32_e32 v59, v56
	s_waitcnt vmcnt(20)
	v_mul_f32_e32 v56, v9, v9
	v_mul_f32_e32 v58, v11, v11
	v_pk_add_f32 v[70:71], v[76:77], v[70:71]
	v_pk_add_f32 v[68:69], v[68:69], v[74:75]
	v_mul_f32_e32 v47, v0, v0
	v_mul_f32_e32 v49, v1, v1
	v_mul_f32_e32 v55, v2, v2
	v_mul_f32_e32 v80, v3, v3
	v_pk_fma_f32 v[72:73], v[8:9], v[8:9], v[56:57] op_sel_hi:[1,1,0]
	v_pk_fma_f32 v[78:79], v[10:11], v[10:11], v[58:59] op_sel_hi:[1,1,0]
	v_pk_add_f32 v[70:71], v[70:71], v[70:71] op_sel:[0,1] op_sel_hi:[1,0]
	v_pk_add_f32 v[68:69], v[68:69], v[68:69] op_sel:[0,1] op_sel_hi:[1,0]
	v_mov_b32_e32 v73, v55
	v_mov_b32_e32 v79, v80
	v_mov_b32_e32 v71, v47
	v_mov_b32_e32 v69, v49
	v_pk_add_f32 v[72:73], v[72:73], v[78:79]
	v_pk_add_f32 v[68:69], v[70:71], v[68:69]
	s_waitcnt vmcnt(0)
	v_pk_add_f32 v[62:63], v[88:89], 1.0 op_sel_hi:[1,0]
	v_pk_add_f32 v[68:69], v[68:69], v[72:73]
	v_pk_add_f32 v[60:61], v[86:87], 1.0 op_sel_hi:[1,0]
	v_mov_b32_e32 v58, v68
	v_mov_b32_e32 v56, v69
	v_pk_add_f32 v[56:57], v[58:59], v[56:57]
	s_nop 1
	v_mov_b32_dpp v59, v57 quad_perm:[1,0,3,2] row_mask:0xf bank_mask:0xf bound_ctrl:1
	v_mov_b32_dpp v58, v56 quad_perm:[1,0,3,2] row_mask:0xf bank_mask:0xf bound_ctrl:1
	v_pk_add_f32 v[56:57], v[56:57], v[58:59]
	s_nop 1
	v_mov_b32_dpp v59, v57 quad_perm:[2,3,0,1] row_mask:0xf bank_mask:0xf bound_ctrl:1
	v_mov_b32_dpp v58, v56 quad_perm:[2,3,0,1] row_mask:0xf bank_mask:0xf bound_ctrl:1
	v_pk_add_f32 v[56:57], v[56:57], v[58:59]
	s_nop 1
	v_mov_b32_dpp v59, v57 row_half_mirror row_mask:0xf bank_mask:0xf bound_ctrl:1
	v_mov_b32_dpp v58, v56 row_half_mirror row_mask:0xf bank_mask:0xf bound_ctrl:1
	v_pk_add_f32 v[56:57], v[56:57], v[58:59]
	s_nop 1
	v_mov_b32_dpp v59, v57 row_mirror row_mask:0xf bank_mask:0xf bound_ctrl:1
	v_mov_b32_dpp v58, v56 row_mirror row_mask:0xf bank_mask:0xf bound_ctrl:1
	v_pk_add_f32 v[56:57], v[56:57], v[58:59]
	ds_bpermute_b32 v59, v41, v57
	ds_bpermute_b32 v58, v41, v56
	s_waitcnt lgkmcnt(0)
; __device__ __forceinline__ unsigned pk2(float a, float b) { typedef __bf16 bf2_t __attribute__((ext_vector_type(2))); f32x2 v = {a, b}; return __builtin_bit_cast(unsigned, __builtin_convertvector(v, bf2_t)); }
; __device__ __forceinline__ void phase_normmod(const float* X, const float* g, const float* mod, int sh_off, int sc_off, bf16* U, int lane, int gw, int NGW, int rowEnd = MT) {
;     ...
;         const float ra = rsqrtf(sa * (1.f / DM) + 1e-6f), rb = rsqrtf(sb * (1.f / DM) + 1e-6f);
;         const float* ma = mod + (size_t)(row >> 13) * NMODC; const float* mb = mod + (size_t)(rB >> 13) * NMODC;
; #pragma unroll
;         for (int j = 0; j < 4; ++j) { const int col = 4 * lane + 256 * j; const f32x4 gv = *(const f32x4*)(g + col);
;             { const f32x4 sc = *(const f32x4*)(ma + sc_off + col), sh = *(const f32x4*)(ma + sh_off + col); const f32x4 o = (va[j] * ra * gv) * (sc + 1.f) + sh; u32x2 w; w.x = pk2(o.x, o.y); w.y = pk2(o.z, o.w); *(u32x2*)(U + (size_t)row * DM + col) = w; }
;             if (has2) { const f32x4 sc = *(const f32x4*)(mb + sc_off + col), sh = *(const f32x4*)(mb + sh_off + col); const f32x4 o = (vb[j] * rb * gv) * (sc + 1.f) + sh; u32x2 w; w.x = pk2(o.x, o.y); w.y = pk2(o.z, o.w); *(u32x2*)(U + (size_t)rB * DM + col) = w; } }
	v_pk_add_f32 v[56:57], v[56:57], v[58:59]
	ds_bpermute_b32 v59, v45, v57
	ds_bpermute_b32 v58, v45, v56
	s_waitcnt lgkmcnt(0)
	v_pk_add_f32 v[56:57], v[56:57], v[58:59]
	s_nop 0
	v_pk_fma_f32 v[56:57], v[56:57], s[14:15], v[54:55] op_sel_hi:[1,0,0]
	s_nop 0
	v_mul_f32_e32 v47, 0x4b800000, v57
	v_cmp_gt_f32_e32 vcc, s5, v57
	v_mul_f32_e32 v49, 0x4b800000, v56
	v_cmp_gt_f32_e64 s[2:3], s5, v56
	v_cndmask_b32_e32 v47, v57, v47, vcc
	v_rsq_f32_e32 v47, v47
	v_cndmask_b32_e64 v49, v56, v49, s[2:3]
	v_rsq_f32_e32 v49, v49
	v_mul_f32_e32 v55, 0x45800000, v47
	v_cndmask_b32_e32 v58, v47, v55, vcc
	v_pk_mul_f32 v[30:31], v[30:31], v[58:59] op_sel_hi:[1,0]
	v_pk_mul_f32 v[28:29], v[28:29], v[58:59] op_sel_hi:[1,0]
	v_mul_f32_e32 v56, 0x45800000, v49
	v_pk_mul_f32 v[28:29], v[82:83], v[28:29]
	v_pk_mul_f32 v[30:31], v[84:85], v[30:31]
	v_cndmask_b32_e64 v56, v49, v56, s[2:3]
	v_pk_fma_f32 v[30:31], v[62:63], v[30:31], v[92:93]
	v_pk_fma_f32 v[28:29], v[60:61], v[28:29], v[90:91]
	v_mov_b32_e32 v57, v56
	v_cvt_pk_bf16_f32 v28, v28, v29
	v_cvt_pk_bf16_f32 v29, v30, v31
	v_lshlrev_b32_e32 v47, 1, v40
	global_store_dwordx2 v[50:51], v[28:29], off
	s_cbranch_scc1 .LBB0_593
	v_mov_b32_e32 v64, v56
	v_mov_b32_e32 v65, v56
	v_pk_mul_f32 v[24:25], v[24:25], v[56:57]
	v_pk_mul_f32 v[26:27], v[26:27], v[64:65]
	v_pk_mul_f32 v[24:25], v[82:83], v[24:25]
	v_pk_mul_f32 v[26:27], v[84:85], v[26:27]
	v_pk_add_f32 v[30:31], v[96:97], 1.0 op_sel_hi:[1,0]
	v_pk_add_f32 v[28:29], v[94:95], 1.0 op_sel_hi:[1,0]
	v_pk_fma_f32 v[26:27], v[26:27], v[30:31], v[100:101]
	v_pk_fma_f32 v[24:25], v[24:25], v[28:29], v[98:99]
	s_nop 0
	v_cvt_pk_bf16_f32 v24, v24, v25
	v_cvt_pk_bf16_f32 v25, v26, v27
	global_store_dwordx2 v47, v[24:25], s[20:21]
.LBB0_593:
	v_lshlrev_b32_e32 v32, 2, v44
	v_lshl_add_u64 v[28:29], s[24:25], 0, v[36:37]
	v_mov_b32_e32 v59, v58
	v_mov_b32_e32 v30, v58
	v_mov_b32_e32 v31, v58
	v_pk_mul_f32 v[22:23], v[22:23], v[30:31]
	v_pk_mul_f32 v[20:21], v[20:21], v[58:59]
	v_cndmask_b32_e64 v33, 0, 1, s[0:1]
	v_cmp_ne_u32_e64 s[2:3], 1, v33
	s_andn2_b64 vcc, exec, s[0:1]
	v_pk_mul_f32 v[22:23], v[22:23], v[104:105]
	v_pk_mul_f32 v[20:21], v[20:21], v[102:103]
	v_pk_add_f32 v[34:35], v[108:109], 1.0 op_sel_hi:[1,0]
	v_pk_add_f32 v[60:61], v[106:107], 1.0 op_sel_hi:[1,0]
	v_pk_fma_f32 v[22:23], v[22:23], v[34:35], v[114:115]
	v_pk_fma_f32 v[20:21], v[20:21], v[60:61], v[112:113]
	s_nop 0
	v_cvt_pk_bf16_f32 v20, v20, v21
	v_cvt_pk_bf16_f32 v21, v22, v23
	global_store_dwordx2 v[50:51], v[20:21], off offset:512
	s_cbranch_vccnz .LBB0_595
	s_nop 0
	v_mov_b32_e32 v60, v56
	v_mov_b32_e32 v61, v56
	v_pk_mul_f32 v[16:17], v[16:17], v[56:57]
	v_pk_mul_f32 v[18:19], v[18:19], v[60:61]
	v_pk_mul_f32 v[16:17], v[16:17], v[102:103]
	v_pk_mul_f32 v[18:19], v[18:19], v[104:105]
	v_pk_add_f32 v[22:23], v[120:121], 1.0 op_sel_hi:[1,0]
	v_pk_add_f32 v[20:21], v[118:119], 1.0 op_sel_hi:[1,0]
	v_pk_fma_f32 v[18:19], v[18:19], v[22:23], v[126:127]
	v_pk_fma_f32 v[16:17], v[16:17], v[20:21], v[124:125]
	s_nop 0
	v_cvt_pk_bf16_f32 v16, v16, v17
	v_cvt_pk_bf16_f32 v17, v18, v19
	global_store_dwordx2 v47, v[16:17], s[20:21] offset:512
.LBB0_595:
	v_lshlrev_b32_e32 v20, 2, v46
	v_pk_mul_f32 v[14:15], v[14:15], v[30:31]
	v_pk_mul_f32 v[12:13], v[12:13], v[58:59]
	s_and_b64 vcc, exec, s[2:3]
	v_pk_mul_f32 v[14:15], v[14:15], v[154:155]
	v_pk_mul_f32 v[12:13], v[12:13], v[152:153]
	v_pk_add_f32 v[24:25], v[158:159], 1.0 op_sel_hi:[1,0]
	v_pk_add_f32 v[22:23], v[156:157], 1.0 op_sel_hi:[1,0]
	v_pk_fma_f32 v[14:15], v[14:15], v[24:25], v[170:171]
	v_pk_fma_f32 v[12:13], v[12:13], v[22:23], v[168:169]
	s_nop 0
	v_cvt_pk_bf16_f32 v12, v12, v13
	v_cvt_pk_bf16_f32 v13, v14, v15
	global_store_dwordx2 v[50:51], v[12:13], off offset:1024
	s_cbranch_vccnz .LBB0_597
	s_nop 0
	v_mov_b32_e32 v24, v56
	v_mov_b32_e32 v25, v56
	v_pk_mul_f32 v[8:9], v[8:9], v[56:57]
	v_pk_mul_f32 v[10:11], v[10:11], v[24:25]
	v_pk_mul_f32 v[8:9], v[8:9], v[152:153]
	v_pk_mul_f32 v[10:11], v[10:11], v[154:155]
	v_pk_add_f32 v[14:15], v[174:175], 1.0 op_sel_hi:[1,0]
	v_pk_add_f32 v[12:13], v[172:173], 1.0 op_sel_hi:[1,0]
	v_pk_fma_f32 v[10:11], v[10:11], v[14:15], v[180:181]
	v_pk_fma_f32 v[8:9], v[8:9], v[12:13], v[178:179]
	s_nop 0
	v_cvt_pk_bf16_f32 v8, v8, v9
	v_cvt_pk_bf16_f32 v9, v10, v11
	global_store_dwordx2 v47, v[8:9], s[20:21] offset:1024
.LBB0_597:
	v_lshlrev_b32_e32 v12, 2, v48
	v_mov_b32_e32 v22, v58
	v_mov_b32_e32 v23, v58
	v_pk_mul_f32 v[4:5], v[4:5], v[58:59]
	v_pk_mul_f32 v[6:7], v[6:7], v[22:23]
	s_and_b64 vcc, exec, s[2:3]
	v_pk_mul_f32 v[6:7], v[6:7], v[184:185]
	v_pk_mul_f32 v[4:5], v[4:5], v[182:183]
	v_pk_add_f32 v[16:17], v[188:189], 1.0 op_sel_hi:[1,0]
	v_pk_add_f32 v[14:15], v[186:187], 1.0 op_sel_hi:[1,0]
	v_pk_fma_f32 v[6:7], v[6:7], v[16:17], v[194:195]
	v_pk_fma_f32 v[4:5], v[4:5], v[14:15], v[192:193]
	s_nop 0
	v_cvt_pk_bf16_f32 v4, v4, v5
	v_cvt_pk_bf16_f32 v5, v6, v7
	global_store_dwordx2 v[50:51], v[4:5], off offset:1536
	s_cbranch_vccnz .LBB0_590
	s_nop 0
	v_mov_b32_e32 v16, v56
	v_mov_b32_e32 v17, v56
	v_pk_mul_f32 v[0:1], v[0:1], v[56:57]
	v_pk_mul_f32 v[2:3], v[2:3], v[16:17]
	v_pk_mul_f32 v[0:1], v[0:1], v[182:183]
	v_pk_mul_f32 v[2:3], v[2:3], v[184:185]
	v_pk_add_f32 v[6:7], v[200:201], 1.0 op_sel_hi:[1,0]
	v_pk_add_f32 v[4:5], v[198:199], 1.0 op_sel_hi:[1,0]
	v_pk_fma_f32 v[2:3], v[2:3], v[6:7], v[206:207]
	v_pk_fma_f32 v[0:1], v[0:1], v[4:5], v[204:205]
	s_nop 0
	v_cvt_pk_bf16_f32 v0, v0, v1
	v_cvt_pk_bf16_f32 v1, v2, v3
	global_store_dwordx2 v47, v[0:1], s[20:21] offset:1536
	s_branch .LBB0_590

; __device__ __forceinline__ unsigned pk2(float a, float b) { typedef __bf16 bf2_t __attribute__((ext_vector_type(2))); f32x2 v = {a, b}; return __builtin_bit_cast(unsigned, __builtin_convertvector(v, bf2_t)); }
; __device__ __forceinline__ void phase_normmod(const float* X, const float* g, const float* mod, int sh_off, int sc_off, bf16* U, int lane, int gw, int NGW, int rowEnd = MT) {
; #pragma unroll 1
;     for (int row = gw; row < rowEnd; row += 2 * NGW) { const int row2 = row + NGW;
;         const bool has2 = row2 < rowEnd; const int rB = has2 ? row2 : row;
;         const f32x4* xa = (const f32x4*)(X + (size_t)row * DM) + lane; const f32x4* xb = (const f32x4*)(X + (size_t)rB * DM) + lane; f32x4 va[4], vb[4]; float sa = 0.f, sb = 0.f;
; #pragma unroll
;         for (int j = 0; j < 4; ++j) { va[j] = xa[64 * j]; vb[j] = xb[64 * j]; }
; #pragma unroll
;         for (int j = 0; j < 4; ++j) { sa += (va[j].x * va[j].x + va[j].y * va[j].y) + (va[j].z * va[j].z + va[j].w * va[j].w); sb += (vb[j].x * vb[j].x + vb[j].y * vb[j].y) + (vb[j].z * vb[j].z + vb[j].w * vb[j].w); }
;         wave_sum2(sa, sb);
;         const float ra = rsqrtf(sa * (1.f / DM) + 1e-6f), rb = rsqrtf(sb * (1.f / DM) + 1e-6f);
;         const float* ma = mod + (size_t)(row >> 13) * NMODC; const float* mb = mod + (size_t)(rB >> 13) * NMODC;
; #pragma unroll
;         for (int j = 0; j < 4; ++j) { const int col = 4 * lane + 256 * j; const f32x4 gv = *(const f32x4*)(g + col);
;             { const f32x4 sc = *(const f32x4*)(ma + sc_off + col), sh = *(const f32x4*)(ma + sh_off + col); const f32x4 o = (va[j] * ra * gv) * (sc + 1.f) + sh; u32x2 w; w.x = pk2(o.x, o.y); w.y = pk2(o.z, o.w); *(u32x2*)(U + (size_t)row * DM + col) = w; }
;             if (has2) { const f32x4 sc = *(const f32x4*)(mb + sc_off + col), sh = *(const f32x4*)(mb + sh_off + col); const f32x4 o = (vb[j] * rb * gv) * (sc + 1.f) + sh; u32x2 w; w.x = pk2(o.x, o.y); w.y = pk2(o.z, o.w); *(u32x2*)(U + (size_t)rB * DM + col) = w; } }
.LBB0_808:
	s_add_i32 s11, s94, s4
	global_load_dwordx4 v[28:31], v[50:51], off
	global_load_dwordx4 v[20:23], v[50:51], off offset:1024
	global_load_dwordx4 v[4:7], v[50:51], off offset:3072
	global_load_dwordx4 v[12:15], v[50:51], off offset:2048
	s_cmp_lt_i32 s11, 0x10000
	s_cselect_b64 s[0:1], -1, 0
	s_and_b64 s[2:3], s[0:1], exec
	s_cselect_b32 s2, s11, s4
	s_ashr_i32 s3, s2, 31
	s_lshl_b64 s[14:15], s[2:3], 12
	v_lshl_add_u64 v[8:9], v[36:37], 0, s[14:15]
	global_load_dwordx4 v[24:27], v[8:9], off
	global_load_dwordx4 v[16:19], v[8:9], off offset:1024
	global_load_dwordx4 v[0:3], v[8:9], off offset:3072
	s_nop 0
	global_load_dwordx4 v[8:11], v[8:9], off offset:2048
	s_nop 0
	s_ashr_i32 s14, s4, 13
	s_mul_hi_i32 s15, s14, 0x9000
	s_mul_i32 s14, s14, 0x9000
	s_add_u32 s16, s84, s14
	s_addc_u32 s17, s85, s15
	s_ashr_i32 s14, s2, 13
	s_mul_hi_i32 s15, s14, 0x9000
	s_mul_i32 s14, s14, 0x9000
	s_add_u32 s18, s84, s14
	s_addc_u32 s19, s85, s15
	s_add_u32 s14, s16, 0x4000
	s_addc_u32 s15, s17, 0
	s_add_u32 s16, s16, 0x3000
	s_addc_u32 s17, s17, 0
	s_add_u32 s20, s18, 0x4000
	s_addc_u32 s21, s19, 0
	s_add_u32 s22, s18, 0x3000
	s_addc_u32 s23, s19, 0
	s_lshl_b64 s[2:3], s[2:3], 11
	s_add_u32 s18, s58, s2
	s_addc_u32 s19, s59, s3
	s_cmp_gt_i32 s11, 0xffff
	global_load_dwordx4 v[82:85], v[40:41], off
	global_load_dwordx4 v[86:89], v45, s[14:15]
	global_load_dwordx4 v[90:93], v45, s[16:17]
	global_load_dwordx4 v[94:97], v45, s[20:21]
	global_load_dwordx4 v[98:101], v45, s[22:23]
	global_load_dwordx4 v[102:105], v[40:41], off offset:1024
	v_lshlrev_b32_e32 v110, 2, v42
	global_load_dwordx4 v[106:109], v110, s[14:15]
	v_lshlrev_b32_e32 v116, 2, v42
	global_load_dwordx4 v[112:115], v116, s[16:17]
	v_lshlrev_b32_e32 v122, 2, v42
	global_load_dwordx4 v[118:121], v122, s[20:21]
	v_lshlrev_b32_e32 v152, 2, v42
	global_load_dwordx4 v[124:127], v152, s[22:23]
	global_load_dwordx4 v[154:157], v[40:41], off offset:2048
	v_lshlrev_b32_e32 v162, 2, v44
	global_load_dwordx4 v[158:161], v162, s[14:15]
	v_lshlrev_b32_e32 v172, 2, v44
	global_load_dwordx4 v[168:171], v172, s[16:17]
	v_lshlrev_b32_e32 v178, 2, v44
	global_load_dwordx4 v[174:177], v178, s[20:21]
	v_lshlrev_b32_e32 v184, 2, v44
	global_load_dwordx4 v[180:183], v184, s[22:23]
	global_load_dwordx4 v[186:189], v[40:41], off offset:3072
	v_lshlrev_b32_e32 v194, 2, v46
	global_load_dwordx4 v[190:193], v194, s[14:15]
	v_lshlrev_b32_e32 v200, 2, v46
	global_load_dwordx4 v[196:199], v200, s[16:17]
	v_lshlrev_b32_e32 v206, 2, v46
	global_load_dwordx4 v[202:205], v206, s[20:21]
	v_lshlrev_b32_e32 v212, 2, v46
	global_load_dwordx4 v[208:211], v212, s[22:23]
	s_waitcnt vmcnt(27)
	v_pk_mul_f32 v[54:55], v[30:31], v[30:31]
	v_pk_mul_f32 v[56:57], v[28:29], v[28:29]
	s_waitcnt vmcnt(26)
	v_pk_mul_f32 v[66:67], v[22:23], v[22:23]
	v_pk_mul_f32 v[68:69], v[20:21], v[20:21]
	v_pk_mov_b32 v[74:75], v[56:57], v[54:55] op_sel:[1,0]
	v_mov_b32_e32 v57, v55
	v_pk_mov_b32 v[54:55], v[68:69], v[66:67] op_sel:[1,0]
	v_mov_b32_e32 v69, v67
	s_waitcnt vmcnt(25)
	v_mul_f32_e32 v73, v6, v6
	s_waitcnt vmcnt(24)
	v_mul_f32_e32 v70, v13, v13
	v_mul_f32_e32 v72, v15, v15
	v_pk_add_f32 v[56:57], v[74:75], v[56:57]
	v_pk_add_f32 v[54:55], v[54:55], v[68:69]
	v_mul_f32_e32 v47, v4, v4
	v_mul_f32_e32 v53, v5, v5
	v_mul_f32_e32 v76, v7, v7
	v_pk_fma_f32 v[66:67], v[12:13], v[12:13], v[70:71] op_sel_hi:[1,1,0]
	v_pk_fma_f32 v[70:71], v[14:15], v[14:15], v[72:73] op_sel_hi:[1,1,0]
	v_pk_add_f32 v[56:57], v[56:57], v[56:57] op_sel:[0,1] op_sel_hi:[1,0]
	v_pk_add_f32 v[54:55], v[54:55], v[54:55] op_sel:[0,1] op_sel_hi:[1,0]
	v_mov_b32_e32 v67, v73
	v_mov_b32_e32 v71, v76
	v_mov_b32_e32 v57, v47
	v_mov_b32_e32 v55, v53
	v_pk_add_f32 v[66:67], v[66:67], v[70:71]
	v_pk_add_f32 v[54:55], v[56:57], v[54:55]
	s_waitcnt vmcnt(23)
	v_pk_mul_f32 v[68:69], v[24:25], v[24:25]
	v_pk_add_f32 v[54:55], v[54:55], v[66:67]
	v_pk_mul_f32 v[66:67], v[26:27], v[26:27]
	s_waitcnt vmcnt(22)
	v_pk_mul_f32 v[70:71], v[18:19], v[18:19]
	v_pk_mul_f32 v[72:73], v[16:17], v[16:17]
	v_pk_mov_b32 v[74:75], v[68:69], v[66:67] op_sel:[1,0]
	v_mov_b32_e32 v69, v67
	v_pk_mov_b32 v[66:67], v[72:73], v[70:71] op_sel:[1,0]
	v_mov_b32_e32 v73, v71
	v_mov_b32_e32 v57, v54
	s_waitcnt vmcnt(20)
	v_mul_f32_e32 v54, v9, v9
	v_mul_f32_e32 v56, v11, v11
	v_pk_add_f32 v[68:69], v[74:75], v[68:69]
	v_pk_add_f32 v[66:67], v[66:67], v[72:73]
	v_mul_f32_e32 v47, v0, v0
	v_mul_f32_e32 v53, v1, v1
	v_mul_f32_e32 v78, v2, v2
	v_mul_f32_e32 v79, v3, v3
	v_pk_fma_f32 v[70:71], v[8:9], v[8:9], v[54:55] op_sel_hi:[1,1,0]
	v_pk_fma_f32 v[76:77], v[10:11], v[10:11], v[56:57] op_sel_hi:[1,1,0]
	v_pk_add_f32 v[68:69], v[68:69], v[68:69] op_sel:[0,1] op_sel_hi:[1,0]
	v_pk_add_f32 v[66:67], v[66:67], v[66:67] op_sel:[0,1] op_sel_hi:[1,0]
	v_mov_b32_e32 v71, v78
	v_mov_b32_e32 v77, v79
	v_mov_b32_e32 v69, v47
	v_mov_b32_e32 v67, v53
	v_pk_add_f32 v[70:71], v[70:71], v[76:77]
	v_pk_add_f32 v[66:67], v[68:69], v[66:67]
	s_waitcnt vmcnt(0)
	v_pk_add_f32 v[60:61], v[88:89], 1.0 op_sel_hi:[1,0]
	v_pk_add_f32 v[66:67], v[66:67], v[70:71]
	v_pk_add_f32 v[58:59], v[86:87], 1.0 op_sel_hi:[1,0]
	v_mov_b32_e32 v56, v66
	v_mov_b32_e32 v54, v67
	v_pk_add_f32 v[54:55], v[56:57], v[54:55]
	s_nop 1
	v_mov_b32_dpp v57, v55 quad_perm:[1,0,3,2] row_mask:0xf bank_mask:0xf bound_ctrl:1
	v_mov_b32_dpp v56, v54 quad_perm:[1,0,3,2] row_mask:0xf bank_mask:0xf bound_ctrl:1
	v_pk_add_f32 v[54:55], v[54:55], v[56:57]
	s_nop 1
	v_mov_b32_dpp v57, v55 quad_perm:[2,3,0,1] row_mask:0xf bank_mask:0xf bound_ctrl:1
	v_mov_b32_dpp v56, v54 quad_perm:[2,3,0,1] row_mask:0xf bank_mask:0xf bound_ctrl:1
	v_pk_add_f32 v[54:55], v[54:55], v[56:57]
	s_nop 1
	v_mov_b32_dpp v57, v55 row_half_mirror row_mask:0xf bank_mask:0xf bound_ctrl:1
	v_mov_b32_dpp v56, v54 row_half_mirror row_mask:0xf bank_mask:0xf bound_ctrl:1
	v_pk_add_f32 v[54:55], v[54:55], v[56:57]
	s_nop 1
	v_mov_b32_dpp v57, v55 row_mirror row_mask:0xf bank_mask:0xf bound_ctrl:1
	v_mov_b32_dpp v56, v54 row_mirror row_mask:0xf bank_mask:0xf bound_ctrl:1
	v_pk_add_f32 v[54:55], v[54:55], v[56:57]
	ds_bpermute_b32 v57, v39, v55
	ds_bpermute_b32 v56, v39, v54
	s_waitcnt lgkmcnt(0)
; __device__ __forceinline__ unsigned pk2(float a, float b) { typedef __bf16 bf2_t __attribute__((ext_vector_type(2))); f32x2 v = {a, b}; return __builtin_bit_cast(unsigned, __builtin_convertvector(v, bf2_t)); }
; __device__ __forceinline__ void phase_normmod(const float* X, const float* g, const float* mod, int sh_off, int sc_off, bf16* U, int lane, int gw, int NGW, int rowEnd = MT) {
;     ...
;         const float ra = rsqrtf(sa * (1.f / DM) + 1e-6f), rb = rsqrtf(sb * (1.f / DM) + 1e-6f);
;         const float* ma = mod + (size_t)(row >> 13) * NMODC; const float* mb = mod + (size_t)(rB >> 13) * NMODC;
; #pragma unroll
;         for (int j = 0; j < 4; ++j) { const int col = 4 * lane + 256 * j; const f32x4 gv = *(const f32x4*)(g + col);
;             { const f32x4 sc = *(const f32x4*)(ma + sc_off + col), sh = *(const f32x4*)(ma + sh_off + col); const f32x4 o = (va[j] * ra * gv) * (sc + 1.f) + sh; u32x2 w; w.x = pk2(o.x, o.y); w.y = pk2(o.z, o.w); *(u32x2*)(U + (size_t)row * DM + col) = w; }
;             if (has2) { const f32x4 sc = *(const f32x4*)(mb + sc_off + col), sh = *(const f32x4*)(mb + sh_off + col); const f32x4 o = (vb[j] * rb * gv) * (sc + 1.f) + sh; u32x2 w; w.x = pk2(o.x, o.y); w.y = pk2(o.z, o.w); *(u32x2*)(U + (size_t)rB * DM + col) = w; } }
	v_pk_add_f32 v[54:55], v[54:55], v[56:57]
	ds_bpermute_b32 v57, v43, v55
	ds_bpermute_b32 v56, v43, v54
	s_waitcnt lgkmcnt(0)
	v_pk_add_f32 v[54:55], v[54:55], v[56:57]
	s_nop 0
	v_pk_fma_f32 v[54:55], v[54:55], s[10:11], v[52:53] op_sel_hi:[1,0,0]
	s_nop 0
	v_mul_f32_e32 v47, 0x4b800000, v55
	v_cmp_gt_f32_e32 vcc, s5, v55
	v_mul_f32_e32 v53, 0x4b800000, v54
	v_cmp_gt_f32_e64 s[2:3], s5, v54
	v_cndmask_b32_e32 v47, v55, v47, vcc
	v_rsq_f32_e32 v47, v47
	v_cndmask_b32_e64 v53, v54, v53, s[2:3]
	v_rsq_f32_e32 v53, v53
	v_mul_f32_e32 v54, 0x45800000, v47
	v_cndmask_b32_e32 v56, v47, v54, vcc
	v_pk_mul_f32 v[30:31], v[30:31], v[56:57] op_sel_hi:[1,0]
	v_pk_mul_f32 v[28:29], v[28:29], v[56:57] op_sel_hi:[1,0]
	v_mul_f32_e32 v47, 0x45800000, v53
	v_pk_mul_f32 v[28:29], v[82:83], v[28:29]
	v_pk_mul_f32 v[30:31], v[84:85], v[30:31]
	v_cndmask_b32_e64 v54, v53, v47, s[2:3]
	v_pk_fma_f32 v[30:31], v[60:61], v[30:31], v[92:93]
	v_pk_fma_f32 v[28:29], v[58:59], v[28:29], v[90:91]
	v_mov_b32_e32 v55, v54
	v_cvt_pk_bf16_f32 v28, v28, v29
	v_cvt_pk_bf16_f32 v29, v30, v31
	v_lshlrev_b32_e32 v30, 1, v38
	global_store_dwordx2 v[48:49], v[28:29], off
	s_cbranch_scc1 .LBB0_810
	v_mov_b32_e32 v28, v54
	v_mov_b32_e32 v29, v54
	v_pk_mul_f32 v[24:25], v[24:25], v[54:55]
	v_pk_mul_f32 v[26:27], v[26:27], v[28:29]
	v_pk_mul_f32 v[24:25], v[82:83], v[24:25]
	v_pk_mul_f32 v[26:27], v[84:85], v[26:27]
	v_pk_add_f32 v[28:29], v[96:97], 1.0 op_sel_hi:[1,0]
	v_pk_add_f32 v[32:33], v[94:95], 1.0 op_sel_hi:[1,0]
	v_pk_fma_f32 v[26:27], v[26:27], v[28:29], v[100:101]
	v_pk_fma_f32 v[24:25], v[24:25], v[32:33], v[98:99]
	s_nop 0
	v_cvt_pk_bf16_f32 v24, v24, v25
	v_cvt_pk_bf16_f32 v25, v26, v27
	global_store_dwordx2 v30, v[24:25], s[18:19]
.LBB0_810:
	v_lshlrev_b32_e32 v31, 2, v42
	v_mov_b32_e32 v57, v56
	v_mov_b32_e32 v28, v56
	v_mov_b32_e32 v29, v56
	v_pk_mul_f32 v[22:23], v[22:23], v[28:29]
	v_pk_mul_f32 v[20:21], v[20:21], v[56:57]
	v_cndmask_b32_e64 v47, 0, 1, s[0:1]
	v_cmp_ne_u32_e64 s[2:3], 1, v47
	s_andn2_b64 vcc, exec, s[0:1]
	v_pk_mul_f32 v[22:23], v[22:23], v[104:105]
	v_pk_mul_f32 v[20:21], v[20:21], v[102:103]
	v_pk_add_f32 v[34:35], v[108:109], 1.0 op_sel_hi:[1,0]
	v_pk_add_f32 v[32:33], v[106:107], 1.0 op_sel_hi:[1,0]
	v_pk_fma_f32 v[22:23], v[22:23], v[34:35], v[114:115]
	v_pk_fma_f32 v[20:21], v[20:21], v[32:33], v[112:113]
	s_nop 0
	v_cvt_pk_bf16_f32 v20, v20, v21
	v_cvt_pk_bf16_f32 v21, v22, v23
	global_store_dwordx2 v[48:49], v[20:21], off offset:512
	s_cbranch_vccnz .LBB0_812
	v_mov_b32_e32 v58, v54
	v_mov_b32_e32 v59, v54
	v_pk_mul_f32 v[16:17], v[16:17], v[54:55]
	v_pk_mul_f32 v[18:19], v[18:19], v[58:59]
	v_pk_mul_f32 v[16:17], v[16:17], v[102:103]
	v_pk_mul_f32 v[18:19], v[18:19], v[104:105]
	v_pk_add_f32 v[22:23], v[120:121], 1.0 op_sel_hi:[1,0]
	v_pk_add_f32 v[20:21], v[118:119], 1.0 op_sel_hi:[1,0]
	v_pk_fma_f32 v[18:19], v[18:19], v[22:23], v[126:127]
	v_pk_fma_f32 v[16:17], v[16:17], v[20:21], v[124:125]
	s_nop 0
	v_cvt_pk_bf16_f32 v16, v16, v17
	v_cvt_pk_bf16_f32 v17, v18, v19
	global_store_dwordx2 v30, v[16:17], s[18:19] offset:512
.LBB0_812:
	v_lshlrev_b32_e32 v20, 2, v44
	v_pk_mul_f32 v[14:15], v[14:15], v[28:29]
	v_pk_mul_f32 v[12:13], v[12:13], v[56:57]
	s_and_b64 vcc, exec, s[2:3]
	v_pk_mul_f32 v[14:15], v[14:15], v[156:157]
	v_pk_mul_f32 v[12:13], v[12:13], v[154:155]
	v_pk_add_f32 v[24:25], v[160:161], 1.0 op_sel_hi:[1,0]
	v_pk_add_f32 v[22:23], v[158:159], 1.0 op_sel_hi:[1,0]
	v_pk_fma_f32 v[14:15], v[14:15], v[24:25], v[170:171]
	v_pk_fma_f32 v[12:13], v[12:13], v[22:23], v[168:169]
	s_nop 0
	v_cvt_pk_bf16_f32 v12, v12, v13
	v_cvt_pk_bf16_f32 v13, v14, v15
	global_store_dwordx2 v[48:49], v[12:13], off offset:1024
	s_cbranch_vccnz .LBB0_814
	s_nop 0
	v_mov_b32_e32 v24, v54
	v_mov_b32_e32 v25, v54
	v_pk_mul_f32 v[8:9], v[8:9], v[54:55]
	v_pk_mul_f32 v[10:11], v[10:11], v[24:25]
	v_pk_mul_f32 v[8:9], v[8:9], v[154:155]
	v_pk_mul_f32 v[10:11], v[10:11], v[156:157]
	v_pk_add_f32 v[14:15], v[176:177], 1.0 op_sel_hi:[1,0]
	v_pk_add_f32 v[12:13], v[174:175], 1.0 op_sel_hi:[1,0]
	v_pk_fma_f32 v[10:11], v[10:11], v[14:15], v[182:183]
	v_pk_fma_f32 v[8:9], v[8:9], v[12:13], v[180:181]
	s_nop 0
	v_cvt_pk_bf16_f32 v8, v8, v9
	v_cvt_pk_bf16_f32 v9, v10, v11
	global_store_dwordx2 v30, v[8:9], s[18:19] offset:1024
.LBB0_814:
	v_lshlrev_b32_e32 v12, 2, v46
	v_mov_b32_e32 v22, v56
	v_mov_b32_e32 v23, v56
	v_pk_mul_f32 v[4:5], v[4:5], v[56:57]
	v_pk_mul_f32 v[6:7], v[6:7], v[22:23]
	s_and_b64 vcc, exec, s[2:3]
	v_pk_mul_f32 v[6:7], v[6:7], v[188:189]
	v_pk_mul_f32 v[4:5], v[4:5], v[186:187]
	v_pk_add_f32 v[16:17], v[192:193], 1.0 op_sel_hi:[1,0]
	v_pk_add_f32 v[14:15], v[190:191], 1.0 op_sel_hi:[1,0]
	v_pk_fma_f32 v[6:7], v[6:7], v[16:17], v[198:199]
	v_pk_fma_f32 v[4:5], v[4:5], v[14:15], v[196:197]
	s_nop 0
	v_cvt_pk_bf16_f32 v4, v4, v5
	v_cvt_pk_bf16_f32 v5, v6, v7
	global_store_dwordx2 v[48:49], v[4:5], off offset:1536
	s_cbranch_vccnz .LBB0_807
	s_nop 0
	v_mov_b32_e32 v16, v54
	v_mov_b32_e32 v17, v54
	v_pk_mul_f32 v[0:1], v[0:1], v[54:55]
	v_pk_mul_f32 v[2:3], v[2:3], v[16:17]
	v_pk_mul_f32 v[0:1], v[0:1], v[186:187]
	v_pk_mul_f32 v[2:3], v[2:3], v[188:189]
	v_pk_add_f32 v[6:7], v[204:205], 1.0 op_sel_hi:[1,0]
	v_pk_add_f32 v[4:5], v[202:203], 1.0 op_sel_hi:[1,0]
	v_pk_fma_f32 v[2:3], v[2:3], v[6:7], v[210:211]
	v_pk_fma_f32 v[0:1], v[0:1], v[4:5], v[208:209]
	s_nop 0
	v_cvt_pk_bf16_f32 v0, v0, v1
	v_cvt_pk_bf16_f32 v1, v2, v3
	global_store_dwordx2 v30, v[0:1], s[18:19] offset:1536
	s_branch .LBB0_807

; __device__ __forceinline__ unsigned pk2(float a, float b) { typedef __bf16 bf2_t __attribute__((ext_vector_type(2))); f32x2 v = {a, b}; return __builtin_bit_cast(unsigned, __builtin_convertvector(v, bf2_t)); }
; __device__ __forceinline__ void phase_normmod(const float* X, const float* g, const float* mod, int sh_off, int sc_off, bf16* U, int lane, int gw, int NGW, int rowEnd = MT) {
; #pragma unroll 1
;     for (int row = gw; row < rowEnd; row += 2 * NGW) { const int row2 = row + NGW;
;         const bool has2 = row2 < rowEnd; const int rB = has2 ? row2 : row;
;         const f32x4* xa = (const f32x4*)(X + (size_t)row * DM) + lane; const f32x4* xb = (const f32x4*)(X + (size_t)rB * DM) + lane; f32x4 va[4], vb[4]; float sa = 0.f, sb = 0.f;
; #pragma unroll
;         for (int j = 0; j < 4; ++j) { va[j] = xa[64 * j]; vb[j] = xb[64 * j]; }
; #pragma unroll
;         for (int j = 0; j < 4; ++j) { sa += (va[j].x * va[j].x + va[j].y * va[j].y) + (va[j].z * va[j].z + va[j].w * va[j].w); sb += (vb[j].x * vb[j].x + vb[j].y * vb[j].y) + (vb[j].z * vb[j].z + vb[j].w * vb[j].w); }
;         wave_sum2(sa, sb);
;         const float ra = rsqrtf(sa * (1.f / DM) + 1e-6f), rb = rsqrtf(sb * (1.f / DM) + 1e-6f);
;         const float* ma = mod + (size_t)(row >> 13) * NMODC; const float* mb = mod + (size_t)(rB >> 13) * NMODC;
; #pragma unroll
;         for (int j = 0; j < 4; ++j) { const int col = 4 * lane + 256 * j; const f32x4 gv = *(const f32x4*)(g + col);
;             { const f32x4 sc = *(const f32x4*)(ma + sc_off + col), sh = *(const f32x4*)(ma + sh_off + col); const f32x4 o = (va[j] * ra * gv) * (sc + 1.f) + sh; u32x2 w; w.x = pk2(o.x, o.y); w.y = pk2(o.z, o.w); *(u32x2*)(U + (size_t)row * DM + col) = w; }
;             if (has2) { const f32x4 sc = *(const f32x4*)(mb + sc_off + col), sh = *(const f32x4*)(mb + sh_off + col); const f32x4 o = (vb[j] * rb * gv) * (sc + 1.f) + sh; u32x2 w; w.x = pk2(o.x, o.y); w.y = pk2(o.z, o.w); *(u32x2*)(U + (size_t)rB * DM + col) = w; } }
.LBB0_1677:
	s_add_i32 s13, s94, s6
	global_load_dwordx4 v[28:31], v[50:51], off
	global_load_dwordx4 v[20:23], v[50:51], off offset:1024
	global_load_dwordx4 v[4:7], v[50:51], off offset:3072
	global_load_dwordx4 v[12:15], v[50:51], off offset:2048
	s_cmp_lt_i32 s13, 0x10000
	s_cselect_b64 s[0:1], -1, 0
	s_and_b64 s[4:5], s[0:1], exec
	s_cselect_b32 s4, s13, s6
	s_ashr_i32 s5, s4, 31
	s_lshl_b64 s[14:15], s[4:5], 12
	v_lshl_add_u64 v[54:55], v[36:37], 0, s[14:15]
	global_load_dwordx4 v[24:27], v[54:55], off
	global_load_dwordx4 v[16:19], v[54:55], off offset:1024
	global_load_dwordx4 v[0:3], v[54:55], off offset:3072
	global_load_dwordx4 v[8:11], v[54:55], off offset:2048
	s_ashr_i32 s14, s6, 13
	s_mul_hi_i32 s15, s14, 0x9000
	s_mul_i32 s14, s14, 0x9000
	s_add_u32 s16, s76, s14
	s_addc_u32 s17, s77, s15
	s_ashr_i32 s14, s4, 13
	s_mul_hi_i32 s15, s14, 0x9000
	s_mul_i32 s14, s14, 0x9000
	s_add_u32 s18, s76, s14
	s_addc_u32 s19, s77, s15
	s_add_u32 s14, s16, 0x7000
	s_addc_u32 s15, s17, 0
	s_add_u32 s16, s16, 0x6000
	s_addc_u32 s17, s17, 0
	s_add_u32 s20, s18, 0x7000
	s_addc_u32 s21, s19, 0
	s_add_u32 s22, s18, 0x6000
	s_addc_u32 s23, s19, 0
	s_lshl_b64 s[4:5], s[4:5], 11
	s_add_u32 s18, s42, s4
	s_addc_u32 s19, s43, s5
	s_cmp_gt_i32 s13, 0xffff
	global_load_dwordx4 v[82:85], v[40:41], off
	global_load_dwordx4 v[86:89], v45, s[14:15]
	global_load_dwordx4 v[90:93], v45, s[16:17]
	global_load_dwordx4 v[94:97], v45, s[20:21]
	global_load_dwordx4 v[98:101], v45, s[22:23]
	global_load_dwordx4 v[102:105], v[40:41], off offset:1024
	v_lshlrev_b32_e32 v110, 2, v42
	global_load_dwordx4 v[106:109], v110, s[14:15]
	v_lshlrev_b32_e32 v116, 2, v42
	global_load_dwordx4 v[112:115], v116, s[16:17]
	v_lshlrev_b32_e32 v122, 2, v42
	global_load_dwordx4 v[118:121], v122, s[20:21]
	v_lshlrev_b32_e32 v152, 2, v42
	global_load_dwordx4 v[124:127], v152, s[22:23]
	global_load_dwordx4 v[154:157], v[40:41], off offset:2048
	v_lshlrev_b32_e32 v162, 2, v44
	global_load_dwordx4 v[158:161], v162, s[14:15]
	v_lshlrev_b32_e32 v172, 2, v44
	global_load_dwordx4 v[168:171], v172, s[16:17]
	v_lshlrev_b32_e32 v178, 2, v44
	global_load_dwordx4 v[174:177], v178, s[20:21]
	v_lshlrev_b32_e32 v184, 2, v44
	global_load_dwordx4 v[180:183], v184, s[22:23]
	global_load_dwordx4 v[186:189], v[40:41], off offset:3072
	v_lshlrev_b32_e32 v194, 2, v46
	global_load_dwordx4 v[190:193], v194, s[14:15]
	v_lshlrev_b32_e32 v200, 2, v46
	global_load_dwordx4 v[196:199], v200, s[16:17]
	v_lshlrev_b32_e32 v206, 2, v46
	global_load_dwordx4 v[202:205], v206, s[20:21]
	v_lshlrev_b32_e32 v212, 2, v46
	global_load_dwordx4 v[208:211], v212, s[22:23]
	s_waitcnt vmcnt(27)
	v_pk_mul_f32 v[54:55], v[30:31], v[30:31]
	v_pk_mul_f32 v[56:57], v[28:29], v[28:29]
	s_waitcnt vmcnt(26)
	v_pk_mul_f32 v[66:67], v[22:23], v[22:23]
	v_pk_mul_f32 v[68:69], v[20:21], v[20:21]
	v_pk_mov_b32 v[74:75], v[56:57], v[54:55] op_sel:[1,0]
	v_mov_b32_e32 v57, v55
	v_pk_mov_b32 v[54:55], v[68:69], v[66:67] op_sel:[1,0]
	v_mov_b32_e32 v69, v67
	s_waitcnt vmcnt(25)
	v_mul_f32_e32 v73, v6, v6
	s_waitcnt vmcnt(24)
	v_mul_f32_e32 v70, v13, v13
	v_mul_f32_e32 v72, v15, v15
	v_pk_add_f32 v[56:57], v[74:75], v[56:57]
	v_pk_add_f32 v[54:55], v[54:55], v[68:69]
	v_mul_f32_e32 v47, v4, v4
	v_mul_f32_e32 v53, v5, v5
	v_mul_f32_e32 v76, v7, v7
	v_pk_fma_f32 v[66:67], v[12:13], v[12:13], v[70:71] op_sel_hi:[1,1,0]
	v_pk_fma_f32 v[70:71], v[14:15], v[14:15], v[72:73] op_sel_hi:[1,1,0]
	v_pk_add_f32 v[56:57], v[56:57], v[56:57] op_sel:[0,1] op_sel_hi:[1,0]
	v_pk_add_f32 v[54:55], v[54:55], v[54:55] op_sel:[0,1] op_sel_hi:[1,0]
	v_mov_b32_e32 v67, v73
	v_mov_b32_e32 v71, v76
	v_mov_b32_e32 v57, v47
	v_mov_b32_e32 v55, v53
	v_pk_add_f32 v[66:67], v[66:67], v[70:71]
	v_pk_add_f32 v[54:55], v[56:57], v[54:55]
	s_waitcnt vmcnt(23)
	v_pk_mul_f32 v[68:69], v[24:25], v[24:25]
	v_pk_add_f32 v[54:55], v[54:55], v[66:67]
	v_pk_mul_f32 v[66:67], v[26:27], v[26:27]
	s_waitcnt vmcnt(22)
	v_pk_mul_f32 v[70:71], v[18:19], v[18:19]
	v_pk_mul_f32 v[72:73], v[16:17], v[16:17]
	v_pk_mov_b32 v[74:75], v[68:69], v[66:67] op_sel:[1,0]
	v_mov_b32_e32 v69, v67
	v_pk_mov_b32 v[66:67], v[72:73], v[70:71] op_sel:[1,0]
	v_mov_b32_e32 v73, v71
	v_mov_b32_e32 v57, v54
	s_waitcnt vmcnt(20)
	v_mul_f32_e32 v54, v9, v9
	v_mul_f32_e32 v56, v11, v11
	v_pk_add_f32 v[68:69], v[74:75], v[68:69]
	v_pk_add_f32 v[66:67], v[66:67], v[72:73]
	v_mul_f32_e32 v47, v0, v0
	v_mul_f32_e32 v53, v1, v1
	v_mul_f32_e32 v78, v2, v2
	v_mul_f32_e32 v79, v3, v3
	v_pk_fma_f32 v[70:71], v[8:9], v[8:9], v[54:55] op_sel_hi:[1,1,0]
	v_pk_fma_f32 v[76:77], v[10:11], v[10:11], v[56:57] op_sel_hi:[1,1,0]
	v_pk_add_f32 v[68:69], v[68:69], v[68:69] op_sel:[0,1] op_sel_hi:[1,0]
	v_pk_add_f32 v[66:67], v[66:67], v[66:67] op_sel:[0,1] op_sel_hi:[1,0]
	v_mov_b32_e32 v71, v78
	v_mov_b32_e32 v77, v79
	v_mov_b32_e32 v69, v47
	v_mov_b32_e32 v67, v53
	v_pk_add_f32 v[70:71], v[70:71], v[76:77]
	v_pk_add_f32 v[66:67], v[68:69], v[66:67]
	s_waitcnt vmcnt(0)
	v_pk_add_f32 v[60:61], v[88:89], 1.0 op_sel_hi:[1,0]
	v_pk_add_f32 v[66:67], v[66:67], v[70:71]
	v_pk_add_f32 v[58:59], v[86:87], 1.0 op_sel_hi:[1,0]
	v_mov_b32_e32 v56, v66
	v_mov_b32_e32 v54, v67
	v_pk_add_f32 v[54:55], v[56:57], v[54:55]
	s_nop 1
	v_mov_b32_dpp v57, v55 quad_perm:[1,0,3,2] row_mask:0xf bank_mask:0xf bound_ctrl:1
	v_mov_b32_dpp v56, v54 quad_perm:[1,0,3,2] row_mask:0xf bank_mask:0xf bound_ctrl:1
	v_pk_add_f32 v[54:55], v[54:55], v[56:57]
	s_nop 1
	v_mov_b32_dpp v57, v55 quad_perm:[2,3,0,1] row_mask:0xf bank_mask:0xf bound_ctrl:1
	v_mov_b32_dpp v56, v54 quad_perm:[2,3,0,1] row_mask:0xf bank_mask:0xf bound_ctrl:1
	v_pk_add_f32 v[54:55], v[54:55], v[56:57]
	s_nop 1
	v_mov_b32_dpp v57, v55 row_half_mirror row_mask:0xf bank_mask:0xf bound_ctrl:1
	v_mov_b32_dpp v56, v54 row_half_mirror row_mask:0xf bank_mask:0xf bound_ctrl:1
	v_pk_add_f32 v[54:55], v[54:55], v[56:57]
	s_nop 1
	v_mov_b32_dpp v57, v55 row_mirror row_mask:0xf bank_mask:0xf bound_ctrl:1
	v_mov_b32_dpp v56, v54 row_mirror row_mask:0xf bank_mask:0xf bound_ctrl:1
	v_pk_add_f32 v[54:55], v[54:55], v[56:57]
	ds_bpermute_b32 v57, v39, v55
	ds_bpermute_b32 v56, v39, v54
	s_waitcnt lgkmcnt(0)
; __device__ __forceinline__ unsigned pk2(float a, float b) { typedef __bf16 bf2_t __attribute__((ext_vector_type(2))); f32x2 v = {a, b}; return __builtin_bit_cast(unsigned, __builtin_convertvector(v, bf2_t)); }
; __device__ __forceinline__ void phase_normmod(const float* X, const float* g, const float* mod, int sh_off, int sc_off, bf16* U, int lane, int gw, int NGW, int rowEnd = MT) {
;     ...
;         const float ra = rsqrtf(sa * (1.f / DM) + 1e-6f), rb = rsqrtf(sb * (1.f / DM) + 1e-6f);
;         const float* ma = mod + (size_t)(row >> 13) * NMODC; const float* mb = mod + (size_t)(rB >> 13) * NMODC;
; #pragma unroll
;         for (int j = 0; j < 4; ++j) { const int col = 4 * lane + 256 * j; const f32x4 gv = *(const f32x4*)(g + col);
;             { const f32x4 sc = *(const f32x4*)(ma + sc_off + col), sh = *(const f32x4*)(ma + sh_off + col); const f32x4 o = (va[j] * ra * gv) * (sc + 1.f) + sh; u32x2 w; w.x = pk2(o.x, o.y); w.y = pk2(o.z, o.w); *(u32x2*)(U + (size_t)row * DM + col) = w; }
;             if (has2) { const f32x4 sc = *(const f32x4*)(mb + sc_off + col), sh = *(const f32x4*)(mb + sh_off + col); const f32x4 o = (vb[j] * rb * gv) * (sc + 1.f) + sh; u32x2 w; w.x = pk2(o.x, o.y); w.y = pk2(o.z, o.w); *(u32x2*)(U + (size_t)rB * DM + col) = w; } }
	v_pk_add_f32 v[54:55], v[54:55], v[56:57]
	ds_bpermute_b32 v57, v43, v55
	ds_bpermute_b32 v56, v43, v54
	s_waitcnt lgkmcnt(0)
	v_pk_add_f32 v[54:55], v[54:55], v[56:57]
	s_nop 0
	v_pk_fma_f32 v[54:55], v[54:55], s[12:13], v[52:53] op_sel_hi:[1,0,0]
	s_nop 0
	v_mul_f32_e32 v47, 0x4b800000, v55
	v_cmp_gt_f32_e32 vcc, s7, v55
	v_mul_f32_e32 v53, 0x4b800000, v54
	v_cmp_gt_f32_e64 s[4:5], s7, v54
	v_cndmask_b32_e32 v47, v55, v47, vcc
	v_rsq_f32_e32 v47, v47
	v_cndmask_b32_e64 v53, v54, v53, s[4:5]
	v_rsq_f32_e32 v53, v53
	v_mul_f32_e32 v54, 0x45800000, v47
	v_cndmask_b32_e32 v56, v47, v54, vcc
	v_pk_mul_f32 v[30:31], v[30:31], v[56:57] op_sel_hi:[1,0]
	v_pk_mul_f32 v[28:29], v[28:29], v[56:57] op_sel_hi:[1,0]
	v_mul_f32_e32 v47, 0x45800000, v53
	v_pk_mul_f32 v[28:29], v[82:83], v[28:29]
	v_pk_mul_f32 v[30:31], v[84:85], v[30:31]
	v_cndmask_b32_e64 v54, v53, v47, s[4:5]
	v_pk_fma_f32 v[30:31], v[60:61], v[30:31], v[92:93]
	v_pk_fma_f32 v[28:29], v[58:59], v[28:29], v[90:91]
	v_mov_b32_e32 v55, v54
	v_cvt_pk_bf16_f32 v28, v28, v29
	v_cvt_pk_bf16_f32 v29, v30, v31
	v_lshlrev_b32_e32 v30, 1, v38
	global_store_dwordx2 v[48:49], v[28:29], off
	s_cbranch_scc1 .LBB0_1679
	v_mov_b32_e32 v28, v54
	v_mov_b32_e32 v29, v54
	v_pk_mul_f32 v[24:25], v[24:25], v[54:55]
	v_pk_mul_f32 v[26:27], v[26:27], v[28:29]
	v_pk_mul_f32 v[24:25], v[82:83], v[24:25]
	v_pk_mul_f32 v[26:27], v[84:85], v[26:27]
	v_pk_add_f32 v[28:29], v[96:97], 1.0 op_sel_hi:[1,0]
	v_pk_add_f32 v[32:33], v[94:95], 1.0 op_sel_hi:[1,0]
	v_pk_fma_f32 v[26:27], v[26:27], v[28:29], v[100:101]
	v_pk_fma_f32 v[24:25], v[24:25], v[32:33], v[98:99]
	s_nop 0
	v_cvt_pk_bf16_f32 v24, v24, v25
	v_cvt_pk_bf16_f32 v25, v26, v27
	global_store_dwordx2 v30, v[24:25], s[18:19]
.LBB0_1679:
	v_lshlrev_b32_e32 v31, 2, v42
	v_mov_b32_e32 v57, v56
	v_mov_b32_e32 v28, v56
	v_mov_b32_e32 v29, v56
	v_pk_mul_f32 v[22:23], v[22:23], v[28:29]
	v_pk_mul_f32 v[20:21], v[20:21], v[56:57]
	v_cndmask_b32_e64 v47, 0, 1, s[0:1]
	v_cmp_ne_u32_e64 s[4:5], 1, v47
	s_andn2_b64 vcc, exec, s[0:1]
	v_pk_mul_f32 v[22:23], v[22:23], v[104:105]
	v_pk_mul_f32 v[20:21], v[20:21], v[102:103]
	v_pk_add_f32 v[34:35], v[108:109], 1.0 op_sel_hi:[1,0]
	v_pk_add_f32 v[32:33], v[106:107], 1.0 op_sel_hi:[1,0]
	v_pk_fma_f32 v[22:23], v[22:23], v[34:35], v[114:115]
	v_pk_fma_f32 v[20:21], v[20:21], v[32:33], v[112:113]
	s_nop 0
	v_cvt_pk_bf16_f32 v20, v20, v21
	v_cvt_pk_bf16_f32 v21, v22, v23
	global_store_dwordx2 v[48:49], v[20:21], off offset:512
	s_cbranch_vccnz .LBB0_1681
	v_mov_b32_e32 v58, v54
	v_mov_b32_e32 v59, v54
	v_pk_mul_f32 v[16:17], v[16:17], v[54:55]
	v_pk_mul_f32 v[18:19], v[18:19], v[58:59]
	v_pk_mul_f32 v[16:17], v[16:17], v[102:103]
	v_pk_mul_f32 v[18:19], v[18:19], v[104:105]
	v_pk_add_f32 v[22:23], v[120:121], 1.0 op_sel_hi:[1,0]
	v_pk_add_f32 v[20:21], v[118:119], 1.0 op_sel_hi:[1,0]
	v_pk_fma_f32 v[18:19], v[18:19], v[22:23], v[126:127]
	v_pk_fma_f32 v[16:17], v[16:17], v[20:21], v[124:125]
	s_nop 0
	v_cvt_pk_bf16_f32 v16, v16, v17
	v_cvt_pk_bf16_f32 v17, v18, v19
	global_store_dwordx2 v30, v[16:17], s[18:19] offset:512
.LBB0_1681:
	v_lshlrev_b32_e32 v20, 2, v44
	v_pk_mul_f32 v[14:15], v[14:15], v[28:29]
	v_pk_mul_f32 v[12:13], v[12:13], v[56:57]
	s_and_b64 vcc, exec, s[4:5]
	v_pk_mul_f32 v[14:15], v[14:15], v[156:157]
	v_pk_mul_f32 v[12:13], v[12:13], v[154:155]
	v_pk_add_f32 v[24:25], v[160:161], 1.0 op_sel_hi:[1,0]
	v_pk_add_f32 v[22:23], v[158:159], 1.0 op_sel_hi:[1,0]
	v_pk_fma_f32 v[14:15], v[14:15], v[24:25], v[170:171]
	v_pk_fma_f32 v[12:13], v[12:13], v[22:23], v[168:169]
	s_nop 0
	v_cvt_pk_bf16_f32 v12, v12, v13
	v_cvt_pk_bf16_f32 v13, v14, v15
	global_store_dwordx2 v[48:49], v[12:13], off offset:1024
	s_cbranch_vccnz .LBB0_1683
	v_mov_b32_e32 v20, v54
	v_mov_b32_e32 v21, v54
	v_pk_mul_f32 v[8:9], v[8:9], v[54:55]
	v_pk_mul_f32 v[10:11], v[10:11], v[20:21]
	v_pk_mul_f32 v[8:9], v[8:9], v[154:155]
	v_pk_mul_f32 v[10:11], v[10:11], v[156:157]
	v_pk_add_f32 v[14:15], v[176:177], 1.0 op_sel_hi:[1,0]
	v_pk_add_f32 v[12:13], v[174:175], 1.0 op_sel_hi:[1,0]
	v_pk_fma_f32 v[10:11], v[10:11], v[14:15], v[182:183]
	v_pk_fma_f32 v[8:9], v[8:9], v[12:13], v[180:181]
	s_nop 0
	v_cvt_pk_bf16_f32 v8, v8, v9
	v_cvt_pk_bf16_f32 v9, v10, v11
	global_store_dwordx2 v30, v[8:9], s[18:19] offset:1024
.LBB0_1683:
	v_lshlrev_b32_e32 v12, 2, v46
	v_mov_b32_e32 v22, v56
	v_mov_b32_e32 v23, v56
	v_pk_mul_f32 v[4:5], v[4:5], v[56:57]
	v_pk_mul_f32 v[6:7], v[6:7], v[22:23]
	s_and_b64 vcc, exec, s[4:5]
	v_pk_mul_f32 v[6:7], v[6:7], v[188:189]
	v_pk_mul_f32 v[4:5], v[4:5], v[186:187]
	v_pk_add_f32 v[16:17], v[192:193], 1.0 op_sel_hi:[1,0]
	v_pk_add_f32 v[14:15], v[190:191], 1.0 op_sel_hi:[1,0]
	v_pk_fma_f32 v[6:7], v[6:7], v[16:17], v[198:199]
	v_pk_fma_f32 v[4:5], v[4:5], v[14:15], v[196:197]
	s_nop 0
	v_cvt_pk_bf16_f32 v4, v4, v5
	v_cvt_pk_bf16_f32 v5, v6, v7
	global_store_dwordx2 v[48:49], v[4:5], off offset:1536
	s_cbranch_vccnz .LBB0_1676
	v_mov_b32_e32 v12, v54
	v_mov_b32_e32 v13, v54
	v_pk_mul_f32 v[0:1], v[0:1], v[54:55]
	v_pk_mul_f32 v[2:3], v[2:3], v[12:13]
	v_pk_mul_f32 v[0:1], v[0:1], v[186:187]
	v_pk_mul_f32 v[2:3], v[2:3], v[188:189]
	v_pk_add_f32 v[6:7], v[204:205], 1.0 op_sel_hi:[1,0]
	v_pk_add_f32 v[4:5], v[202:203], 1.0 op_sel_hi:[1,0]
	v_pk_fma_f32 v[2:3], v[2:3], v[6:7], v[210:211]
	v_pk_fma_f32 v[0:1], v[0:1], v[4:5], v[208:209]
	s_nop 0
	v_cvt_pk_bf16_f32 v0, v0, v1
	v_cvt_pk_bf16_f32 v1, v2, v3
	global_store_dwordx2 v30, v[0:1], s[18:19] offset:1536
	s_branch .LBB0_1676

; __device__ __forceinline__ void phase_finalnorm(float* X, const float* g, int lane, int gw, int NGW, int rowEnd = MT) {
; #pragma unroll 1
;     for (int row = gw; row < rowEnd; row += 2 * NGW) { const int row2 = row + NGW; const bool has2 = row2 < rowEnd; const int rB = has2 ? row2 : row;
;         f32x4* xa = (f32x4*)(X + (size_t)row * DM) + lane; f32x4* xb = (f32x4*)(X + (size_t)rB * DM) + lane; f32x4 va[4], vb[4]; float sa = 0.f, sb = 0.f;
; #pragma unroll
;         for (int j = 0; j < 4; ++j) { va[j] = xa[64 * j]; vb[j] = xb[64 * j]; }
; #pragma unroll
;         for (int j = 0; j < 4; ++j) { sa += (va[j].x * va[j].x + va[j].y * va[j].y) + (va[j].z * va[j].z + va[j].w * va[j].w); sb += (vb[j].x * vb[j].x + vb[j].y * vb[j].y) + (vb[j].z * vb[j].z + vb[j].w * vb[j].w); }
;         wave_sum2(sa, sb);
;         const float ra = rsqrtf(sa * (1.f / DM) + 1e-6f), rb = rsqrtf(sb * (1.f / DM) + 1e-6f);
; #pragma unroll
;         for (int j = 0; j < 4; ++j) { const f32x4 gv = *(const f32x4*)(g + 4 * lane + 256 * j); xa[64 * j] = va[j] * ra * gv; if (has2) xb[64 * j] = vb[j] * rb * gv; }
.LBB0_1885:
	s_or_b64 exec, exec, s[2:3]
	s_waitcnt lgkmcnt(0)
	s_barrier
	v_readlane_b32 s1, v239, 1
	v_readfirstlane_b32 s0, v164
	s_ashr_i32 s0, s0, 6
	s_add_i32 s0, s0, s1
	s_cmp_gt_i32 s0, 0xffff
	s_cbranch_scc1 .LBB0_1896
	v_and_b32_e32 v3, 64, v167
	v_xor_b32_e32 v2, 16, v167
	v_add_u32_e32 v3, 64, v3
	v_cmp_lt_i32_e32 vcc, v2, v3
	v_and_b32_e32 v0, 63, v164
	v_lshlrev_b32_e32 v0, 4, v0
	v_cndmask_b32_e32 v2, v167, v2, vcc
	v_lshlrev_b32_e32 v37, 2, v2
	v_xor_b32_e32 v2, 32, v167
	v_cmp_lt_i32_e32 vcc, v2, v3
	v_mov_b32_e32 v1, 0
	v_lshl_add_u64 v[32:33], s[50:51], 0, v[0:1]
	v_cndmask_b32_e32 v2, v167, v2, vcc
	v_lshlrev_b32_e32 v46, 2, v2
	v_lshl_add_u64 v[34:35], s[48:49], 0, v[0:1]
	s_mov_b32 s4, 0x3a800000
	v_mov_b32_e32 v36, 0x358637bd
	s_mov_b32 s5, 0x800000
	global_load_dwordx4 v[80:83], v[34:35], off
	global_load_dwordx4 v[84:87], v[34:35], off offset:1024
	global_load_dwordx4 v[88:91], v[34:35], off offset:2048
	global_load_dwordx4 v[92:95], v[34:35], off offset:3072
	s_branch .LBB0_1888

; __device__ __forceinline__ void phase_finalnorm(float* X, const float* g, int lane, int gw, int NGW, int rowEnd = MT) {
;     ...
;     for (int row = gw; row < rowEnd; row += 2 * NGW) { const int row2 = row + NGW; const bool has2 = row2 < rowEnd; const int rB = has2 ? row2 : row;
;         f32x4* xa = (f32x4*)(X + (size_t)row * DM) + lane; f32x4* xb = (f32x4*)(X + (size_t)rB * DM) + lane; f32x4 va[4], vb[4]; float sa = 0.f, sb = 0.f;
; #pragma unroll
;         for (int j = 0; j < 4; ++j) { va[j] = xa[64 * j]; vb[j] = xb[64 * j]; }
; #pragma unroll
;         for (int j = 0; j < 4; ++j) { sa += (va[j].x * va[j].x + va[j].y * va[j].y) + (va[j].z * va[j].z + va[j].w * va[j].w); sb += (vb[j].x * vb[j].x + vb[j].y * vb[j].y) + (vb[j].z * vb[j].z + vb[j].w * vb[j].w); }
;         wave_sum2(sa, sb);
;         const float ra = rsqrtf(sa * (1.f / DM) + 1e-6f), rb = rsqrtf(sb * (1.f / DM) + 1e-6f);
; #pragma unroll
;         for (int j = 0; j < 4; ++j) { const f32x4 gv = *(const f32x4*)(g + 4 * lane + 256 * j); xa[64 * j] = va[j] * ra * gv; if (has2) xb[64 * j] = vb[j] * rb * gv; }
;     }
.LBB0_1888:
	s_add_i32 s10, s0, s94
	s_cmp_gt_i32 s10, 0xffff
	s_cselect_b64 s[6:7], -1, 0
	s_cmp_lt_i32 s10, 0x10000
	s_cselect_b32 s2, s10, s0
	s_ashr_i32 s1, s0, 31
	s_lshl_b64 s[0:1], s[0:1], 12
	v_lshl_add_u64 v[38:39], v[32:33], 0, s[0:1]
	global_load_dwordx4 v[48:51], v[38:39], off
	global_load_dwordx4 v[16:19], v[38:39], off offset:1024
	global_load_dwordx4 v[0:3], v[38:39], off offset:3072
	global_load_dwordx4 v[12:15], v[38:39], off offset:2048
	s_ashr_i32 s3, s2, 31
	s_lshl_b64 s[0:1], s[2:3], 12
	v_lshl_add_u64 v[40:41], v[32:33], 0, s[0:1]
	global_load_dwordx4 v[24:27], v[40:41], off
	global_load_dwordx4 v[20:23], v[40:41], off offset:1024
	global_load_dwordx4 v[4:7], v[40:41], off offset:3072
	global_load_dwordx4 v[8:11], v[40:41], off offset:2048
	s_and_b64 s[2:3], exec, s[6:7]
	s_mov_b64 s[8:9], -1
	s_waitcnt vmcnt(7)
	v_pk_mul_f32 v[42:43], v[50:51], v[50:51]
	v_pk_mul_f32 v[44:45], v[48:49], v[48:49]
	s_waitcnt vmcnt(6)
	v_pk_mul_f32 v[52:53], v[18:19], v[18:19]
	v_pk_mul_f32 v[54:55], v[16:17], v[16:17]
	s_waitcnt vmcnt(4)
	v_mul_f32_e32 v56, v13, v13
	v_mul_f32_e32 v58, v15, v15
	v_pk_mov_b32 v[60:61], v[44:45], v[42:43] op_sel:[1,0]
	v_mov_b32_e32 v45, v43
	s_waitcnt vmcnt(3)
	v_pk_mul_f32 v[42:43], v[26:27], v[26:27]
	v_pk_mul_f32 v[62:63], v[24:25], v[24:25]
	v_pk_mov_b32 v[64:65], v[54:55], v[52:53] op_sel:[1,0]
	v_mov_b32_e32 v55, v53
	s_waitcnt vmcnt(2)
	v_pk_mul_f32 v[52:53], v[22:23], v[22:23]
	v_pk_mul_f32 v[66:67], v[20:21], v[20:21]
	v_mul_f32_e32 v71, v2, v2
	v_mul_f32_e32 v72, v3, v3
	v_pk_fma_f32 v[56:57], v[12:13], v[12:13], v[56:57] op_sel_hi:[1,1,0]
	v_pk_fma_f32 v[58:59], v[14:15], v[14:15], v[58:59] op_sel_hi:[1,1,0]
	v_pk_add_f32 v[44:45], v[60:61], v[44:45]
	v_pk_mov_b32 v[60:61], v[62:63], v[42:43] op_sel:[1,0]
	v_mov_b32_e32 v63, v43
	v_pk_add_f32 v[42:43], v[64:65], v[54:55]
	v_pk_mov_b32 v[54:55], v[66:67], v[52:53] op_sel:[1,0]
	v_mov_b32_e32 v67, v53
	v_mul_f32_e32 v69, v1, v1
	s_waitcnt vmcnt(0)
	v_mul_f32_e32 v68, v9, v9
	v_mul_f32_e32 v70, v11, v11
	v_mov_b32_e32 v57, v71
	v_mov_b32_e32 v59, v72
	v_pk_add_f32 v[60:61], v[60:61], v[62:63]
	v_pk_add_f32 v[54:55], v[54:55], v[66:67]
	v_mul_f32_e32 v47, v0, v0
	v_mul_f32_e32 v73, v4, v4
	v_mul_f32_e32 v74, v5, v5
	v_mul_f32_e32 v75, v6, v6
	v_mul_f32_e32 v76, v7, v7
	v_pk_fma_f32 v[52:53], v[8:9], v[8:9], v[68:69] op_sel_hi:[1,1,0]
	v_pk_fma_f32 v[64:65], v[10:11], v[10:11], v[70:71] op_sel_hi:[1,1,0]
	v_pk_add_f32 v[44:45], v[44:45], v[44:45] op_sel:[0,1] op_sel_hi:[1,0]
	v_pk_add_f32 v[42:43], v[42:43], v[42:43] op_sel:[0,1] op_sel_hi:[1,0]
	v_pk_add_f32 v[56:57], v[56:57], v[58:59]
	v_pk_add_f32 v[58:59], v[60:61], v[60:61] op_sel:[0,1] op_sel_hi:[1,0]
	v_pk_add_f32 v[54:55], v[54:55], v[54:55] op_sel:[0,1] op_sel_hi:[1,0]
	v_mov_b32_e32 v53, v75
	v_mov_b32_e32 v65, v76
	v_mov_b32_e32 v45, v47
	v_mov_b32_e32 v43, v69
	v_mov_b32_e32 v59, v73
	v_mov_b32_e32 v55, v74
	v_pk_add_f32 v[52:53], v[52:53], v[64:65]
	v_pk_add_f32 v[42:43], v[44:45], v[42:43]
	v_pk_add_f32 v[44:45], v[58:59], v[54:55]
	v_pk_add_f32 v[42:43], v[42:43], v[56:57]
	v_pk_add_f32 v[44:45], v[44:45], v[52:53]
	v_mov_b32_e32 v53, v42
	v_mov_b32_e32 v52, v44
	v_mov_b32_e32 v42, v45
	v_pk_add_f32 v[42:43], v[52:53], v[42:43]
	s_nop 1
	v_mov_b32_dpp v45, v43 quad_perm:[1,0,3,2] row_mask:0xf bank_mask:0xf bound_ctrl:1
	v_mov_b32_dpp v44, v42 quad_perm:[1,0,3,2] row_mask:0xf bank_mask:0xf bound_ctrl:1
	v_pk_add_f32 v[42:43], v[42:43], v[44:45]
	s_nop 1
	v_mov_b32_dpp v45, v43 quad_perm:[2,3,0,1] row_mask:0xf bank_mask:0xf bound_ctrl:1
	v_mov_b32_dpp v44, v42 quad_perm:[2,3,0,1] row_mask:0xf bank_mask:0xf bound_ctrl:1
	v_pk_add_f32 v[42:43], v[42:43], v[44:45]
	s_nop 1
	v_mov_b32_dpp v45, v43 row_half_mirror row_mask:0xf bank_mask:0xf bound_ctrl:1
	v_mov_b32_dpp v44, v42 row_half_mirror row_mask:0xf bank_mask:0xf bound_ctrl:1
	v_pk_add_f32 v[42:43], v[42:43], v[44:45]
	s_nop 1
	v_mov_b32_dpp v45, v43 row_mirror row_mask:0xf bank_mask:0xf bound_ctrl:1
	v_mov_b32_dpp v44, v42 row_mirror row_mask:0xf bank_mask:0xf bound_ctrl:1
	v_pk_add_f32 v[42:43], v[42:43], v[44:45]
	ds_bpermute_b32 v45, v37, v43
	ds_bpermute_b32 v44, v37, v42
	s_waitcnt lgkmcnt(0)
	v_pk_add_f32 v[42:43], v[42:43], v[44:45]
	ds_bpermute_b32 v45, v46, v43
	ds_bpermute_b32 v44, v46, v42
	s_waitcnt lgkmcnt(0)
	v_pk_add_f32 v[42:43], v[42:43], v[44:45]
	s_nop 0
	v_pk_fma_f32 v[44:45], v[42:43], s[4:5], v[36:37] op_sel_hi:[1,0,0]
	s_nop 0
	v_mul_f32_e32 v42, 0x4b800000, v45
	v_cmp_gt_f32_e32 vcc, s5, v45
	v_cmp_gt_f32_e64 s[0:1], s5, v44
	s_nop 0
	v_cndmask_b32_e32 v42, v45, v42, vcc
	v_rsq_f32_e32 v42, v42
	s_nop 0
	v_mul_f32_e32 v43, 0x45800000, v42
	v_cndmask_b32_e32 v42, v42, v43, vcc
	v_mov_b32_e32 v43, v42
	v_pk_mul_f32 v[48:49], v[48:49], v[42:43] op_sel_hi:[1,0]
	v_pk_mul_f32 v[50:51], v[50:51], v[42:43] op_sel_hi:[1,0]
	v_pk_mul_f32 v[16:17], v[16:17], v[42:43]
	v_pk_mul_f32 v[50:51], v[82:83], v[50:51]
	v_pk_mul_f32 v[48:49], v[80:81], v[48:49]
	s_mov_b64 vcc, s[2:3]
	global_store_dwordx4 v[38:39], v[48:51], off
	s_cbranch_vccz .LBB0_1890
	v_mov_b32_e32 v52, v42
	v_mov_b32_e32 v53, v42
	v_pk_mul_f32 v[52:53], v[18:19], v[52:53]
	s_mov_b64 s[8:9], 0
	v_pk_mul_f32 v[50:51], v[52:53], v[86:87]
	v_pk_mul_f32 v[48:49], v[16:17], v[84:85]
	global_store_dwordx4 v[38:39], v[48:51], off offset:1024
.LBB0_1890:
	v_mul_f32_e32 v45, 0x4b800000, v44
	v_cndmask_b32_e64 v44, v44, v45, s[0:1]
	v_rsq_f32_e32 v44, v44
	s_andn2_b64 vcc, exec, s[8:9]
	v_mul_f32_e32 v45, 0x45800000, v44
	v_cndmask_b32_e64 v44, v44, v45, s[0:1]
	v_mov_b32_e32 v45, v44
	s_cbranch_vccnz .LBB0_1892
	v_mov_b32_e32 v48, v44
	v_mov_b32_e32 v49, v44
	v_pk_mul_f32 v[26:27], v[26:27], v[48:49]
	v_pk_mul_f32 v[24:25], v[24:25], v[44:45]
	v_pk_mul_f32 v[26:27], v[82:83], v[26:27]
	v_pk_mul_f32 v[24:25], v[80:81], v[24:25]
	global_store_dwordx4 v[40:41], v[24:27], off
	v_mov_b32_e32 v28, v42
	v_mov_b32_e32 v29, v42
	v_pk_mul_f32 v[18:19], v[18:19], v[28:29]
	v_pk_mul_f32 v[20:21], v[20:21], v[44:45]
	v_pk_mul_f32 v[22:23], v[22:23], v[48:49]
	v_pk_mul_f32 v[18:19], v[18:19], v[86:87]
	v_pk_mul_f32 v[16:17], v[16:17], v[84:85]
	v_pk_mul_f32 v[22:23], v[22:23], v[86:87]
	v_pk_mul_f32 v[20:21], v[20:21], v[84:85]
	global_store_dwordx4 v[38:39], v[16:19], off offset:1024
	global_store_dwordx4 v[40:41], v[20:23], off offset:1024
.LBB0_1892:
	s_nop 1
	v_mov_b32_e32 v20, v42
	v_mov_b32_e32 v21, v42
	v_pk_mul_f32 v[12:13], v[12:13], v[42:43]
	v_pk_mul_f32 v[14:15], v[14:15], v[20:21]
	s_mov_b64 s[0:1], -1
	s_and_b64 vcc, exec, s[6:7]
	v_pk_mul_f32 v[0:1], v[0:1], v[42:43]
	v_pk_mul_f32 v[14:15], v[14:15], v[90:91]
	v_pk_mul_f32 v[12:13], v[12:13], v[88:89]
	global_store_dwordx4 v[38:39], v[12:15], off offset:2048
	s_cbranch_vccz .LBB0_1894
	v_pk_mul_f32 v[20:21], v[2:3], v[20:21]
	v_pk_mul_f32 v[14:15], v[20:21], v[94:95]
	v_pk_mul_f32 v[12:13], v[0:1], v[92:93]
	global_store_dwordx4 v[38:39], v[12:15], off offset:3072
	s_cbranch_execnz .LBB0_1887
	s_branch .LBB0_1895

; __device__ __forceinline__ void phase_finalnorm(float* X, const float* g, int lane, int gw, int NGW, int rowEnd = MT) {
;     ...
; #pragma unroll
;         for (int j = 0; j < 4; ++j) { const f32x4 gv = *(const f32x4*)(g + 4 * lane + 256 * j); xa[64 * j] = va[j] * ra * gv; if (has2) xb[64 * j] = vb[j] * rb * gv; }
;     }
.LBB0_1895:
	v_mov_b32_e32 v12, v44
	v_mov_b32_e32 v13, v44
	v_pk_mul_f32 v[10:11], v[10:11], v[12:13]
	v_pk_mul_f32 v[8:9], v[8:9], v[44:45]
	v_pk_mul_f32 v[10:11], v[10:11], v[90:91]
	v_pk_mul_f32 v[8:9], v[8:9], v[88:89]
	global_store_dwordx4 v[40:41], v[8:11], off offset:2048
	v_mov_b32_e32 v43, v42
	v_pk_mul_f32 v[2:3], v[2:3], v[42:43]
	v_pk_mul_f32 v[4:5], v[4:5], v[44:45]
	v_pk_mul_f32 v[6:7], v[6:7], v[12:13]
	v_pk_mul_f32 v[2:3], v[2:3], v[94:95]
	v_pk_mul_f32 v[0:1], v[0:1], v[92:93]
	v_pk_mul_f32 v[6:7], v[6:7], v[94:95]
	v_pk_mul_f32 v[4:5], v[4:5], v[92:93]
	global_store_dwordx4 v[38:39], v[0:3], off offset:3072
	global_store_dwordx4 v[40:41], v[4:7], off offset:3072
	s_branch .LBB0_1887
